# phase 0: bias half-blocks take no transpose tiles and no rmsnorm rows (rows redistributed), bias GEMV with 16-byte loads, rmsnorm row loop with prefetch and hoisted gains
# speedup vs baseline: 1.0414x; 1.0042x over previous
; DI void phase0(const Params& p, unsigned char* lds) {
;     const int tid = VTID, lane = tid & 63, w = tid >> 6;
;     const int G = VGRID;
;     unsigned char* ws = p.ws;
;     float* tl = (float*)(lds + VHALF * HALF_LDS);
;     ...
;     {
;         const int c0 = 720, c1 = c0 + 256, c2 = c1 + 704, c3 = c2 + 704, c4 = c3 + 704, c5 = c4 + 128, c6 = c5 + 128, c7 = c6 + 4, c8 = c7 + 4;
;         for (int tb = 0; tb < c8; tb += G) {
;             const bool valid = tb + VBLK < c8; const int t = valid ? tb + VBLK : c8 - 1;
.LBB0_23:
	s_or_b64 exec, exec, s[2:3]
	v_readlane_b32 s2, v238, 10
	s_lshl_b32 s33, s2, 1
	s_add_u32 s6, s88, 0x1985000
	v_lshlrev_b32_e32 v2, 2, v1
	s_addc_u32 s7, s89, 0
	v_and_b32_e32 v34, 60, v2
	v_lshlrev_b32_e32 v2, 4, v1
	s_add_u32 s8, s88, 0x1885000
	v_and_b32_e32 v12, 48, v2
	s_addc_u32 s9, s89, 0
	s_mov_b32 s2, 0x12000
	v_lshrrev_b32_e32 v38, 2, v28
	v_mul_u32_u24_e32 v2, 0x41, v12
	s_add_u32 s10, s88, 0x1305000
	v_mad_u32_u24 v32, v31, s2, 0
	v_lshlrev_b32_e32 v2, 2, v2
	s_waitcnt lgkmcnt(0)
	v_and_b32_e32 v3, 0xfc, v28
	v_lshlrev_b32_e32 v14, 9, v38
	v_mov_b32_e32 v15, 0
	s_addc_u32 s11, s89, 0
	v_readlane_b32 s3, v238, 11
	v_add3_u32 v39, v32, v2, v3
	v_add3_u32 v40, v32, v3, v2
	v_lshlrev_b32_e32 v2, 1, v12
	v_mov_b32_e32 v3, v15
	v_lshl_add_u64 v[4:5], s[88:89], 0, v[14:15]
	s_add_u32 s12, s88, 0x805000
	v_lshl_add_u64 v[2:3], v[4:5], 0, v[2:3]
	s_mov_b64 s[2:3], 0x1a95000
	s_addc_u32 s13, s89, 0
	v_lshrrev_b32_e32 v33, 4, v28
	v_lshlrev_b32_e32 v10, 2, v34
	v_lshl_add_u64 v[16:17], v[2:3], 0, s[2:3]
	s_mov_b64 s[2:3], 0x1a85000
	s_add_u32 s14, s88, 0x605000
	v_add_u32_e32 v6, v32, v10
	v_mul_u32_u24_e32 v7, 0x104, v33
	v_lshl_add_u64 v[18:19], v[2:3], 0, s[2:3]
	s_addc_u32 s15, s89, 0
	v_lshrrev_b32_e32 v3, 5, v1
	v_readlane_b32 s36, v238, 31
	v_bfe_u32 v41, v28, 2, 2
	s_add_u32 s16, s88, 0x5000
	v_lshrrev_b32_e32 v2, 1, v28
	v_and_b32_e32 v3, 4, v3
	v_mov_b32_e32 v11, v15
	v_readlane_b32 s37, v238, 32
	v_readlane_b32 s38, v238, 33
	v_readlane_b32 s39, v238, 34
	v_readlane_b32 s40, v238, 35
	v_readlane_b32 s41, v238, 36
	v_readlane_b32 s42, v238, 37
	v_readlane_b32 s43, v238, 38
	v_readlane_b32 s44, v238, 39
	v_readlane_b32 s45, v238, 40
	v_readlane_b32 s46, v238, 41
	v_readlane_b32 s47, v238, 42
	v_readlane_b32 s48, v238, 43
	v_readlane_b32 s49, v238, 44
	v_readlane_b32 s50, v238, 45
	v_readlane_b32 s51, v238, 46
	v_add_u32_e32 v46, v6, v7
	s_mov_b32 s34, 0
	v_add_u32_e32 v30, s4, v31
	v_subrev_u32_e32 v62, 8, v30
	v_mov_b32_e32 v63, 0x7fff0000
	v_cmp_gt_u32_e64 s[72:73], 8, v30
	s_nop 1
	v_cndmask_b32_e64 v62, v62, v63, s[72:73]

; DI void phase0(const Params& p, unsigned char* lds) {
;     ...
;         const int c0 = 720, c1 = c0 + 256, c2 = c1 + 704, c3 = c2 + 704, c4 = c3 + 704, c5 = c4 + 128, c6 = c5 + 128, c7 = c6 + 4, c8 = c7 + 4;
;         for (int tb = 0; tb < c8; tb += G) {
;             const bool valid = tb + VBLK < c8; const int t = valid ? tb + VBLK : c8 - 1;
	v_or_b32_e32 v35, 16, v33
	v_or_b32_e32 v36, 32, v33
	v_or_b32_e32 v37, 48, v33
	s_addc_u32 s17, s89, 0
	v_and_or_b32 v42, v2, 56, v3
	v_lshlrev_b32_e32 v43, 12, v38
	v_lshlrev_b32_e32 v44, 11, v38
	v_lshl_add_u64 v[20:21], s[46:47], 0, v[10:11]
	v_lshl_add_u64 v[22:23], s[40:41], 0, v[10:11]
	v_or_b32_e32 v11, 4, v41
	v_mov_b32_e32 v45, 0xd17
	s_movk_i32 s35, 0x2cf
	s_movk_i32 s36, 0x3cf
	s_movk_i32 s37, 0x68f
	s_movk_i32 s38, 0x94f
	s_movk_i32 s39, 0xc0f
	s_movk_i32 s40, 0xc8f
	s_movk_i32 s41, 0xd0f
	s_movk_i32 s42, 0xd13
	v_add_u32_e32 v47, 0x1040, v46
	v_add_u32_e32 v48, 0x1048, v46
	v_add_u32_e32 v49, 0x2080, v46
	v_add_u32_e32 v50, 0x2088, v46
	v_add_u32_e32 v51, 0x30c0, v46
	v_add_u32_e32 v52, 0x30c8, v46
	s_movk_i32 s43, 0xffd4
	s_movk_i32 s44, 0xaff
	s_movk_i32 s45, 0xb00
	s_mov_b32 s46, 0xb60b60b7
	s_movk_i32 s47, 0xffd3
	s_movk_i32 s48, 0xb17
	s_movk_i32 s49, 0x2c60
	s_movk_i32 s50, 0xb18
	s_movk_i32 s51, 0x400
	s_movk_i32 s52, 0x280
	s_movk_i32 s53, 0x900
	s_movk_i32 s54, 0xa00
	s_movk_i32 s55, 0xffc3
	s_branch .LBB0_26

; DI void transpose_tile(const float* __restrict__ src, int K, int N, bf16_t* __restrict__ dst, int ldd, int mode, int tile, float* tl, bool valid) {
;     const int nbN = (N + 63) >> 6;
;     const int kb = tile / nbN, nb = tile - kb * nbN;
;     const int t = VTID;
;     if (valid) {
; #pragma unroll
;         for (int i = 0; i < 4; ++i) {
;             const int row = (t >> 4) + 16 * i, c4 = (t & 15) * 4, n = nb * 64 + c4;
;             f32x4 v = {0.f, 0.f, 0.f, 0.f};
;             if (n < N) v = *(const f32x4*)(src + (size_t)(kb * 64 + row) * N + n);
;             float* q = tl + row * 65 + c4;
;             q[0] = v[0]; q[1] = v[1]; q[2] = v[2]; q[3] = v[3];
;         }
;     }
; DI void phase0(const Params& p, unsigned char* lds) {
;     ...
;         for (int tb = 0; tb < c8; tb += G) {
;             const bool valid = tb + VBLK < c8; const int t = valid ? tb + VBLK : c8 - 1;
;             if (t < c0) transpose_tile(p.in[2], 1024, INC, (bf16_t*)(ws + OFF_WINT), 1024, 3, t, tl, valid);
;             else if (t < c1) transpose_tile(p.in[14], 1024, 1024, (bf16_t*)(ws + OFF_WOUTT), 1024, 0, t - c0, tl, valid);
;             else if (t < c2) transpose_tile(p.in[17], 1024, DFF, (bf16_t*)(ws + OFF_WGUT), 1024, 1, t - c1, tl, valid);
;             else if (t < c3) transpose_tile(p.in[18], 1024, DFF, (bf16_t*)(ws + OFF_WGUT), 1024, 2, t - c2, tl, valid);
;             else if (t < c4) transpose_tile(p.in[19], DFF, 1024, (bf16_t*)(ws + OFF_WDT), DFF, 0, t - c3, tl, valid);
;             else if (t < c5) transpose_tile(p.in[9], 2048, 256, (bf16_t*)(ws + OFF_W1T), 2048, 0, t - c4, tl, valid);
;             else if (t < c6) transpose_tile(p.in[12], 2048, 256, (bf16_t*)(ws + OFF_W1T) + 256 * 2048, 2048, 0, t - c5, tl, valid);
;             else if (t < c7) transpose_tile(p.in[10], 256, 64, (bf16_t*)(ws + OFF_W2T), 256, 0, t - c6, tl, valid);
;             else transpose_tile(p.in[13], 256, 64, (bf16_t*)(ws + OFF_W2T) + 128 * 256, 256, 0, t - c7, tl, valid);
.LBB0_25:
	s_or_b64 exec, exec, s[2:3]
	s_add_i32 s34, s34, s33
	s_sub_i32 s34, s34, 8
	s_cmpk_gt_i32 s34, 0xd17
	s_cbranch_scc1 .LBB0_108
.LBB0_26:
	v_add_u32_e32 v2, s34, v62
	s_movk_i32 s2, 0xd18
	v_cmp_gt_i32_e32 vcc, s2, v2
	s_nop 1
	v_cndmask_b32_e32 v2, v45, v2, vcc
	v_cmp_lt_i32_e64 s[4:5], s35, v2
	s_and_saveexec_b64 s[2:3], s[4:5]
	s_xor_b64 s[18:19], exec, s[2:3]
	s_cbranch_execz .LBB0_97
	v_cmp_lt_u32_e64 s[4:5], s36, v2
	s_and_saveexec_b64 s[2:3], s[4:5]
	s_xor_b64 s[20:21], exec, s[2:3]
	s_cbranch_execz .LBB0_90
	v_cmp_lt_u32_e64 s[4:5], s37, v2
	s_and_saveexec_b64 s[2:3], s[4:5]
	s_xor_b64 s[2:3], exec, s[2:3]
	s_cbranch_execz .LBB0_78
	v_cmp_lt_u32_e64 s[4:5], s38, v2
	s_and_saveexec_b64 s[22:23], s[4:5]
	s_xor_b64 s[22:23], exec, s[22:23]
	s_cbranch_execz .LBB0_66
	v_cmp_lt_u32_e64 s[4:5], s39, v2
	s_and_saveexec_b64 s[24:25], s[4:5]
	s_xor_b64 s[24:25], exec, s[24:25]
	s_cbranch_execz .LBB0_59
	v_cmp_lt_u32_e64 s[4:5], s40, v2
	s_and_saveexec_b64 s[26:27], s[4:5]
	s_xor_b64 s[26:27], exec, s[26:27]
	s_cbranch_execz .LBB0_52
	v_cmp_lt_u32_e64 s[4:5], s41, v2
	s_and_saveexec_b64 s[28:29], s[4:5]
	s_xor_b64 s[28:29], exec, s[28:29]
	s_cbranch_execz .LBB0_45
	v_cmp_lt_u32_e64 s[4:5], s42, v2
	s_and_saveexec_b64 s[30:31], s[4:5]
	s_xor_b64 s[4:5], exec, s[30:31]
	s_cbranch_execz .LBB0_39
	v_add_u32_e32 v2, 0xfffff2ec, v2
	s_and_saveexec_b64 s[30:31], vcc
	s_cbranch_execz .LBB0_36
	v_lshlrev_b32_e32 v3, 6, v2
	v_or_b32_e32 v14, v3, v33
	v_lshlrev_b64 v[4:5], 8, v[14:15]
	v_or_b32_e32 v14, v3, v35
	v_lshl_add_u64 v[4:5], v[20:21], 0, v[4:5]
	v_lshlrev_b64 v[6:7], 8, v[14:15]
	v_lshl_add_u64 v[8:9], v[20:21], 0, v[6:7]
	global_load_dwordx4 v[4:7], v[4:5], off
	s_nop 0
	global_load_dwordx4 v[24:27], v[8:9], off
	v_or_b32_e32 v14, v3, v36
	v_lshlrev_b64 v[8:9], 8, v[14:15]
	v_lshl_add_u64 v[8:9], v[20:21], 0, v[8:9]
	v_or_b32_e32 v14, v3, v37
	global_load_dwordx4 v[54:57], v[8:9], off
	v_lshlrev_b64 v[8:9], 8, v[14:15]
	v_lshl_add_u64 v[8:9], v[20:21], 0, v[8:9]
	global_load_dwordx4 v[58:61], v[8:9], off
	s_waitcnt vmcnt(3)
	ds_write2_b32 v46, v4, v5 offset1:1
	ds_write2_b32 v46, v6, v7 offset0:2 offset1:3
	s_waitcnt vmcnt(2)
	ds_write2_b32 v47, v24, v25 offset1:1
	ds_write2_b32 v48, v26, v27 offset1:1
	s_waitcnt vmcnt(1)
	ds_write2_b32 v49, v54, v55 offset1:1
	ds_write2_b32 v50, v56, v57 offset1:1
	s_waitcnt vmcnt(0)
	ds_write2_b32 v51, v58, v59 offset1:1
	ds_write2_b32 v52, v60, v61 offset1:1

; DI void phase0(const Params& p, unsigned char* lds) {
;     ...
;     for (int t = VBLK; t < 8; t += G) {
;         const int kv = t >> 2, cgp = t & 3;
;         const float* pos = p.in[kv ? 11 : 8];
;         const float* w1 = p.in[kv ? 12 : 9];
;         const int c = cgp * 64 + (tid & 63), part = tid >> 6;
;         float acc = 0.f;
;         for (int k = part * 512; k < part * 512 + 512; ++k) acc += pos[k] * w1[(size_t)k * 256 + c];
.LBB0_108:
	v_cmp_gt_i32_e32 vcc, 8, v30
	s_and_saveexec_b64 s[2:3], vcc
	s_cbranch_execz .LBB0_115
	v_readfirstlane_b32 s4, v30
	v_readfirstlane_b32 s5, v28
	v_readlane_b32 s8, v238, 31
	v_readlane_b32 s9, v238, 32
	v_readlane_b32 s10, v238, 33
	v_readlane_b32 s11, v238, 34
	v_readlane_b32 s12, v238, 37
	v_readlane_b32 s13, v238, 38
	v_readlane_b32 s14, v238, 39
	v_readlane_b32 s15, v238, 40
	s_nop 3
	s_lshr_b32 s5, s5, 6
	s_lshr_b32 s6, s4, 2
	s_and_b32 s7, s4, 3
	s_cmp_eq_u32 s6, 0
	s_cselect_b32 s16, s8, s12
	s_cselect_b32 s17, s9, s13
	s_cselect_b32 s18, s10, s14
	s_cselect_b32 s19, s11, s15
	v_and_b32_e32 v62, 15, v13
	v_lshrrev_b32_e32 v63, 4, v13
	s_lshl_b32 s20, s5, 9
	v_lshl_add_u32 v64, v63, 7, s20
	s_lshl_b32 s21, s7, 8
	v_lshlrev_b32_e32 v65, 10, v64
	v_lshl_add_u32 v65, v62, 4, v65
	v_add_u32_e32 v65, s21, v65
	v_add_u32_e32 v234, 0x1000, v65
	v_add_u32_e32 v235, 0x2000, v65
	v_add_u32_e32 v236, 0x3000, v65
	v_lshlrev_b32_e32 v66, 2, v64
	v_mov_b32_e32 v230, 0
	v_mov_b32_e32 v231, 0
	v_mov_b32_e32 v232, 0
	v_mov_b32_e32 v233, 0

; DI void phase0(const Params& p, unsigned char* lds) {
;     ...
;         const int c = cgp * 64 + (tid & 63), part = tid >> 6;
;         float acc = 0.f;
;         for (int k = part * 512; k < part * 512 + 512; ++k) acc += pos[k] * w1[(size_t)k * 256 + c];
	global_load_dwordx4 v[134:137], v66, s[16:17] offset:0
	global_load_dwordx4 v[138:141], v66, s[16:17] offset:16
	global_load_dwordx4 v[142:145], v66, s[16:17] offset:32
	global_load_dwordx4 v[146:149], v66, s[16:17] offset:48
	global_load_dwordx4 v[70:73], v65, s[18:19] offset:0
	global_load_dwordx4 v[74:77], v65, s[18:19] offset:1024
	global_load_dwordx4 v[78:81], v65, s[18:19] offset:2048
	global_load_dwordx4 v[82:85], v65, s[18:19] offset:3072
	global_load_dwordx4 v[86:89], v234, s[18:19] offset:0
	global_load_dwordx4 v[90:93], v234, s[18:19] offset:1024
	global_load_dwordx4 v[94:97], v234, s[18:19] offset:2048
	global_load_dwordx4 v[98:101], v234, s[18:19] offset:3072
	global_load_dwordx4 v[102:105], v235, s[18:19] offset:0
	global_load_dwordx4 v[106:109], v235, s[18:19] offset:1024
	global_load_dwordx4 v[110:113], v235, s[18:19] offset:2048
	global_load_dwordx4 v[114:117], v235, s[18:19] offset:3072
	global_load_dwordx4 v[118:121], v236, s[18:19] offset:0
	global_load_dwordx4 v[122:125], v236, s[18:19] offset:1024
	global_load_dwordx4 v[126:129], v236, s[18:19] offset:2048
	global_load_dwordx4 v[130:133], v236, s[18:19] offset:3072
	s_add_u32 s16, s16, 64
	s_addc_u32 s17, s17, 0
	s_add_u32 s18, s18, 0x4000
	s_addc_u32 s19, s19, 0
	global_load_dwordx4 v[214:217], v66, s[16:17] offset:0
	global_load_dwordx4 v[218:221], v66, s[16:17] offset:16
	global_load_dwordx4 v[222:225], v66, s[16:17] offset:32
	global_load_dwordx4 v[226:229], v66, s[16:17] offset:48
	global_load_dwordx4 v[150:153], v65, s[18:19] offset:0
	global_load_dwordx4 v[154:157], v65, s[18:19] offset:1024
	global_load_dwordx4 v[158:161], v65, s[18:19] offset:2048
	global_load_dwordx4 v[162:165], v65, s[18:19] offset:3072
	global_load_dwordx4 v[166:169], v234, s[18:19] offset:0
	global_load_dwordx4 v[170:173], v234, s[18:19] offset:1024
	global_load_dwordx4 v[174:177], v234, s[18:19] offset:2048
	global_load_dwordx4 v[178:181], v234, s[18:19] offset:3072
	global_load_dwordx4 v[182:185], v235, s[18:19] offset:0
	global_load_dwordx4 v[186:189], v235, s[18:19] offset:1024
	global_load_dwordx4 v[190:193], v235, s[18:19] offset:2048
	global_load_dwordx4 v[194:197], v235, s[18:19] offset:3072
	global_load_dwordx4 v[198:201], v236, s[18:19] offset:0
	global_load_dwordx4 v[202:205], v236, s[18:19] offset:1024
	global_load_dwordx4 v[206:209], v236, s[18:19] offset:2048
	global_load_dwordx4 v[210:213], v236, s[18:19] offset:3072
	s_add_u32 s16, s16, 64
	s_addc_u32 s17, s17, 0
	s_add_u32 s18, s18, 0x4000
	s_addc_u32 s19, s19, 0
	s_waitcnt vmcnt(20)
	v_fmac_f32_e32 v230, v134, v70
	v_fmac_f32_e32 v231, v134, v71
	v_fmac_f32_e32 v232, v134, v72
	v_fmac_f32_e32 v233, v134, v73
	v_fmac_f32_e32 v230, v135, v74
	v_fmac_f32_e32 v231, v135, v75
	v_fmac_f32_e32 v232, v135, v76
	v_fmac_f32_e32 v233, v135, v77
	v_fmac_f32_e32 v230, v136, v78
	v_fmac_f32_e32 v231, v136, v79
	v_fmac_f32_e32 v232, v136, v80
	v_fmac_f32_e32 v233, v136, v81
	v_fmac_f32_e32 v230, v137, v82
	v_fmac_f32_e32 v231, v137, v83
	v_fmac_f32_e32 v232, v137, v84
	v_fmac_f32_e32 v233, v137, v85
	v_fmac_f32_e32 v230, v138, v86
	v_fmac_f32_e32 v231, v138, v87
	v_fmac_f32_e32 v232, v138, v88
	v_fmac_f32_e32 v233, v138, v89
	v_fmac_f32_e32 v230, v139, v90
	v_fmac_f32_e32 v231, v139, v91
	v_fmac_f32_e32 v232, v139, v92
	v_fmac_f32_e32 v233, v139, v93
	v_fmac_f32_e32 v230, v140, v94
	v_fmac_f32_e32 v231, v140, v95
	v_fmac_f32_e32 v232, v140, v96
	v_fmac_f32_e32 v233, v140, v97
	v_fmac_f32_e32 v230, v141, v98
	v_fmac_f32_e32 v231, v141, v99
	v_fmac_f32_e32 v232, v141, v100
	v_fmac_f32_e32 v233, v141, v101
	v_fmac_f32_e32 v230, v142, v102
	v_fmac_f32_e32 v231, v142, v103
	v_fmac_f32_e32 v232, v142, v104
	v_fmac_f32_e32 v233, v142, v105
	v_fmac_f32_e32 v230, v143, v106
	v_fmac_f32_e32 v231, v143, v107
	v_fmac_f32_e32 v232, v143, v108
	v_fmac_f32_e32 v233, v143, v109
	v_fmac_f32_e32 v230, v144, v110
	v_fmac_f32_e32 v231, v144, v111
	v_fmac_f32_e32 v232, v144, v112
	v_fmac_f32_e32 v233, v144, v113
	v_fmac_f32_e32 v230, v145, v114
	v_fmac_f32_e32 v231, v145, v115
	v_fmac_f32_e32 v232, v145, v116
	v_fmac_f32_e32 v233, v145, v117
	v_fmac_f32_e32 v230, v146, v118
	v_fmac_f32_e32 v231, v146, v119
	v_fmac_f32_e32 v232, v146, v120
	v_fmac_f32_e32 v233, v146, v121
	v_fmac_f32_e32 v230, v147, v122
	v_fmac_f32_e32 v231, v147, v123
	v_fmac_f32_e32 v232, v147, v124
	v_fmac_f32_e32 v233, v147, v125
	v_fmac_f32_e32 v230, v148, v126
	v_fmac_f32_e32 v231, v148, v127
	v_fmac_f32_e32 v232, v148, v128
	v_fmac_f32_e32 v233, v148, v129
	v_fmac_f32_e32 v230, v149, v130
	v_fmac_f32_e32 v231, v149, v131
	v_fmac_f32_e32 v232, v149, v132
	v_fmac_f32_e32 v233, v149, v133
	global_load_dwordx4 v[134:137], v66, s[16:17] offset:0
	global_load_dwordx4 v[138:141], v66, s[16:17] offset:16
	global_load_dwordx4 v[142:145], v66, s[16:17] offset:32
	global_load_dwordx4 v[146:149], v66, s[16:17] offset:48
	global_load_dwordx4 v[70:73], v65, s[18:19] offset:0
	global_load_dwordx4 v[74:77], v65, s[18:19] offset:1024
	global_load_dwordx4 v[78:81], v65, s[18:19] offset:2048
	global_load_dwordx4 v[82:85], v65, s[18:19] offset:3072
	global_load_dwordx4 v[86:89], v234, s[18:19] offset:0
	global_load_dwordx4 v[90:93], v234, s[18:19] offset:1024
	global_load_dwordx4 v[94:97], v234, s[18:19] offset:2048
	global_load_dwordx4 v[98:101], v234, s[18:19] offset:3072
	global_load_dwordx4 v[102:105], v235, s[18:19] offset:0
	global_load_dwordx4 v[106:109], v235, s[18:19] offset:1024
	global_load_dwordx4 v[110:113], v235, s[18:19] offset:2048
	global_load_dwordx4 v[114:117], v235, s[18:19] offset:3072
	global_load_dwordx4 v[118:121], v236, s[18:19] offset:0
	global_load_dwordx4 v[122:125], v236, s[18:19] offset:1024
	global_load_dwordx4 v[126:129], v236, s[18:19] offset:2048
	global_load_dwordx4 v[130:133], v236, s[18:19] offset:3072
	s_add_u32 s16, s16, 64
	s_addc_u32 s17, s17, 0
	s_add_u32 s18, s18, 0x4000
	s_addc_u32 s19, s19, 0
	s_waitcnt vmcnt(20)
; DI void phase0(const Params& p, unsigned char* lds) {
;     ...
;         const int c = cgp * 64 + (tid & 63), part = tid >> 6;
;         float acc = 0.f;
;         for (int k = part * 512; k < part * 512 + 512; ++k) acc += pos[k] * w1[(size_t)k * 256 + c];
	v_fmac_f32_e32 v230, v214, v150
	v_fmac_f32_e32 v231, v214, v151
	v_fmac_f32_e32 v232, v214, v152
	v_fmac_f32_e32 v233, v214, v153
	v_fmac_f32_e32 v230, v215, v154
	v_fmac_f32_e32 v231, v215, v155
	v_fmac_f32_e32 v232, v215, v156
	v_fmac_f32_e32 v233, v215, v157
	v_fmac_f32_e32 v230, v216, v158
	v_fmac_f32_e32 v231, v216, v159
	v_fmac_f32_e32 v232, v216, v160
	v_fmac_f32_e32 v233, v216, v161
	v_fmac_f32_e32 v230, v217, v162
	v_fmac_f32_e32 v231, v217, v163
	v_fmac_f32_e32 v232, v217, v164
	v_fmac_f32_e32 v233, v217, v165
	v_fmac_f32_e32 v230, v218, v166
	v_fmac_f32_e32 v231, v218, v167
	v_fmac_f32_e32 v232, v218, v168
	v_fmac_f32_e32 v233, v218, v169
	v_fmac_f32_e32 v230, v219, v170
	v_fmac_f32_e32 v231, v219, v171
	v_fmac_f32_e32 v232, v219, v172
	v_fmac_f32_e32 v233, v219, v173
	v_fmac_f32_e32 v230, v220, v174
	v_fmac_f32_e32 v231, v220, v175
	v_fmac_f32_e32 v232, v220, v176
	v_fmac_f32_e32 v233, v220, v177
	v_fmac_f32_e32 v230, v221, v178
	v_fmac_f32_e32 v231, v221, v179
	v_fmac_f32_e32 v232, v221, v180
	v_fmac_f32_e32 v233, v221, v181
	v_fmac_f32_e32 v230, v222, v182
	v_fmac_f32_e32 v231, v222, v183
	v_fmac_f32_e32 v232, v222, v184
	v_fmac_f32_e32 v233, v222, v185
	v_fmac_f32_e32 v230, v223, v186
	v_fmac_f32_e32 v231, v223, v187
	v_fmac_f32_e32 v232, v223, v188
	v_fmac_f32_e32 v233, v223, v189
	v_fmac_f32_e32 v230, v224, v190
	v_fmac_f32_e32 v231, v224, v191
	v_fmac_f32_e32 v232, v224, v192
	v_fmac_f32_e32 v233, v224, v193
	v_fmac_f32_e32 v230, v225, v194
	v_fmac_f32_e32 v231, v225, v195
	v_fmac_f32_e32 v232, v225, v196
	v_fmac_f32_e32 v233, v225, v197
	v_fmac_f32_e32 v230, v226, v198
	v_fmac_f32_e32 v231, v226, v199
	v_fmac_f32_e32 v232, v226, v200
	v_fmac_f32_e32 v233, v226, v201
	v_fmac_f32_e32 v230, v227, v202
	v_fmac_f32_e32 v231, v227, v203
	v_fmac_f32_e32 v232, v227, v204
	v_fmac_f32_e32 v233, v227, v205
	v_fmac_f32_e32 v230, v228, v206
	v_fmac_f32_e32 v231, v228, v207
	v_fmac_f32_e32 v232, v228, v208
	v_fmac_f32_e32 v233, v228, v209
	v_fmac_f32_e32 v230, v229, v210
	v_fmac_f32_e32 v231, v229, v211
	v_fmac_f32_e32 v232, v229, v212
	v_fmac_f32_e32 v233, v229, v213
	global_load_dwordx4 v[214:217], v66, s[16:17] offset:0
	global_load_dwordx4 v[218:221], v66, s[16:17] offset:16
	global_load_dwordx4 v[222:225], v66, s[16:17] offset:32
	global_load_dwordx4 v[226:229], v66, s[16:17] offset:48
	global_load_dwordx4 v[150:153], v65, s[18:19] offset:0
	global_load_dwordx4 v[154:157], v65, s[18:19] offset:1024
	global_load_dwordx4 v[158:161], v65, s[18:19] offset:2048
	global_load_dwordx4 v[162:165], v65, s[18:19] offset:3072
	global_load_dwordx4 v[166:169], v234, s[18:19] offset:0
	global_load_dwordx4 v[170:173], v234, s[18:19] offset:1024
	global_load_dwordx4 v[174:177], v234, s[18:19] offset:2048
	global_load_dwordx4 v[178:181], v234, s[18:19] offset:3072
	global_load_dwordx4 v[182:185], v235, s[18:19] offset:0
	global_load_dwordx4 v[186:189], v235, s[18:19] offset:1024
	global_load_dwordx4 v[190:193], v235, s[18:19] offset:2048
	global_load_dwordx4 v[194:197], v235, s[18:19] offset:3072
	global_load_dwordx4 v[198:201], v236, s[18:19] offset:0
	global_load_dwordx4 v[202:205], v236, s[18:19] offset:1024
	global_load_dwordx4 v[206:209], v236, s[18:19] offset:2048
	global_load_dwordx4 v[210:213], v236, s[18:19] offset:3072
	s_add_u32 s16, s16, 64
	s_addc_u32 s17, s17, 0
	s_add_u32 s18, s18, 0x4000
	s_addc_u32 s19, s19, 0
	s_waitcnt vmcnt(20)
	v_fmac_f32_e32 v230, v134, v70
	v_fmac_f32_e32 v231, v134, v71
	v_fmac_f32_e32 v232, v134, v72
	v_fmac_f32_e32 v233, v134, v73
	v_fmac_f32_e32 v230, v135, v74
	v_fmac_f32_e32 v231, v135, v75
	v_fmac_f32_e32 v232, v135, v76
	v_fmac_f32_e32 v233, v135, v77
	v_fmac_f32_e32 v230, v136, v78
	v_fmac_f32_e32 v231, v136, v79
	v_fmac_f32_e32 v232, v136, v80
	v_fmac_f32_e32 v233, v136, v81
	v_fmac_f32_e32 v230, v137, v82
	v_fmac_f32_e32 v231, v137, v83
	v_fmac_f32_e32 v232, v137, v84
	v_fmac_f32_e32 v233, v137, v85
	v_fmac_f32_e32 v230, v138, v86
	v_fmac_f32_e32 v231, v138, v87
	v_fmac_f32_e32 v232, v138, v88
	v_fmac_f32_e32 v233, v138, v89
	v_fmac_f32_e32 v230, v139, v90
	v_fmac_f32_e32 v231, v139, v91
	v_fmac_f32_e32 v232, v139, v92
	v_fmac_f32_e32 v233, v139, v93
	v_fmac_f32_e32 v230, v140, v94
	v_fmac_f32_e32 v231, v140, v95
	v_fmac_f32_e32 v232, v140, v96
	v_fmac_f32_e32 v233, v140, v97
	v_fmac_f32_e32 v230, v141, v98
	v_fmac_f32_e32 v231, v141, v99
	v_fmac_f32_e32 v232, v141, v100
	v_fmac_f32_e32 v233, v141, v101
	v_fmac_f32_e32 v230, v142, v102
	v_fmac_f32_e32 v231, v142, v103
	v_fmac_f32_e32 v232, v142, v104
	v_fmac_f32_e32 v233, v142, v105
	v_fmac_f32_e32 v230, v143, v106
	v_fmac_f32_e32 v231, v143, v107
	v_fmac_f32_e32 v232, v143, v108
	v_fmac_f32_e32 v233, v143, v109
	v_fmac_f32_e32 v230, v144, v110
	v_fmac_f32_e32 v231, v144, v111
	v_fmac_f32_e32 v232, v144, v112
	v_fmac_f32_e32 v233, v144, v113
	v_fmac_f32_e32 v230, v145, v114
	v_fmac_f32_e32 v231, v145, v115
	v_fmac_f32_e32 v232, v145, v116
	v_fmac_f32_e32 v233, v145, v117
	v_fmac_f32_e32 v230, v146, v118
	v_fmac_f32_e32 v231, v146, v119
	v_fmac_f32_e32 v232, v146, v120
	v_fmac_f32_e32 v233, v146, v121
	v_fmac_f32_e32 v230, v147, v122
	v_fmac_f32_e32 v231, v147, v123
	v_fmac_f32_e32 v232, v147, v124
	v_fmac_f32_e32 v233, v147, v125
	v_fmac_f32_e32 v230, v148, v126
	v_fmac_f32_e32 v231, v148, v127
	v_fmac_f32_e32 v232, v148, v128
	v_fmac_f32_e32 v233, v148, v129
	v_fmac_f32_e32 v230, v149, v130
	v_fmac_f32_e32 v231, v149, v131
	v_fmac_f32_e32 v232, v149, v132
	v_fmac_f32_e32 v233, v149, v133
	global_load_dwordx4 v[134:137], v66, s[16:17] offset:0
	global_load_dwordx4 v[138:141], v66, s[16:17] offset:16
	global_load_dwordx4 v[142:145], v66, s[16:17] offset:32
	global_load_dwordx4 v[146:149], v66, s[16:17] offset:48
	global_load_dwordx4 v[70:73], v65, s[18:19] offset:0
	global_load_dwordx4 v[74:77], v65, s[18:19] offset:1024
	global_load_dwordx4 v[78:81], v65, s[18:19] offset:2048
	global_load_dwordx4 v[82:85], v65, s[18:19] offset:3072
	global_load_dwordx4 v[86:89], v234, s[18:19] offset:0
	global_load_dwordx4 v[90:93], v234, s[18:19] offset:1024
	global_load_dwordx4 v[94:97], v234, s[18:19] offset:2048
	global_load_dwordx4 v[98:101], v234, s[18:19] offset:3072
	global_load_dwordx4 v[102:105], v235, s[18:19] offset:0
	global_load_dwordx4 v[106:109], v235, s[18:19] offset:1024
	global_load_dwordx4 v[110:113], v235, s[18:19] offset:2048
	global_load_dwordx4 v[114:117], v235, s[18:19] offset:3072
	global_load_dwordx4 v[118:121], v236, s[18:19] offset:0
	global_load_dwordx4 v[122:125], v236, s[18:19] offset:1024
	global_load_dwordx4 v[126:129], v236, s[18:19] offset:2048
	global_load_dwordx4 v[130:133], v236, s[18:19] offset:3072
	s_add_u32 s16, s16, 64
	s_addc_u32 s17, s17, 0
	s_add_u32 s18, s18, 0x4000
	s_addc_u32 s19, s19, 0
	s_waitcnt vmcnt(20)
; DI void phase0(const Params& p, unsigned char* lds) {
;     ...
;         const int c = cgp * 64 + (tid & 63), part = tid >> 6;
;         float acc = 0.f;
;         for (int k = part * 512; k < part * 512 + 512; ++k) acc += pos[k] * w1[(size_t)k * 256 + c];
	v_fmac_f32_e32 v230, v214, v150
	v_fmac_f32_e32 v231, v214, v151
	v_fmac_f32_e32 v232, v214, v152
	v_fmac_f32_e32 v233, v214, v153
	v_fmac_f32_e32 v230, v215, v154
	v_fmac_f32_e32 v231, v215, v155
	v_fmac_f32_e32 v232, v215, v156
	v_fmac_f32_e32 v233, v215, v157
	v_fmac_f32_e32 v230, v216, v158
	v_fmac_f32_e32 v231, v216, v159
	v_fmac_f32_e32 v232, v216, v160
	v_fmac_f32_e32 v233, v216, v161
	v_fmac_f32_e32 v230, v217, v162
	v_fmac_f32_e32 v231, v217, v163
	v_fmac_f32_e32 v232, v217, v164
	v_fmac_f32_e32 v233, v217, v165
	v_fmac_f32_e32 v230, v218, v166
	v_fmac_f32_e32 v231, v218, v167
	v_fmac_f32_e32 v232, v218, v168
	v_fmac_f32_e32 v233, v218, v169
	v_fmac_f32_e32 v230, v219, v170
	v_fmac_f32_e32 v231, v219, v171
	v_fmac_f32_e32 v232, v219, v172
	v_fmac_f32_e32 v233, v219, v173
	v_fmac_f32_e32 v230, v220, v174
	v_fmac_f32_e32 v231, v220, v175
	v_fmac_f32_e32 v232, v220, v176
	v_fmac_f32_e32 v233, v220, v177
	v_fmac_f32_e32 v230, v221, v178
	v_fmac_f32_e32 v231, v221, v179
	v_fmac_f32_e32 v232, v221, v180
	v_fmac_f32_e32 v233, v221, v181
	v_fmac_f32_e32 v230, v222, v182
	v_fmac_f32_e32 v231, v222, v183
	v_fmac_f32_e32 v232, v222, v184
	v_fmac_f32_e32 v233, v222, v185
	v_fmac_f32_e32 v230, v223, v186
	v_fmac_f32_e32 v231, v223, v187
	v_fmac_f32_e32 v232, v223, v188
	v_fmac_f32_e32 v233, v223, v189
	v_fmac_f32_e32 v230, v224, v190
	v_fmac_f32_e32 v231, v224, v191
	v_fmac_f32_e32 v232, v224, v192
	v_fmac_f32_e32 v233, v224, v193
	v_fmac_f32_e32 v230, v225, v194
	v_fmac_f32_e32 v231, v225, v195
	v_fmac_f32_e32 v232, v225, v196
	v_fmac_f32_e32 v233, v225, v197
	v_fmac_f32_e32 v230, v226, v198
	v_fmac_f32_e32 v231, v226, v199
	v_fmac_f32_e32 v232, v226, v200
	v_fmac_f32_e32 v233, v226, v201
	v_fmac_f32_e32 v230, v227, v202
	v_fmac_f32_e32 v231, v227, v203
	v_fmac_f32_e32 v232, v227, v204
	v_fmac_f32_e32 v233, v227, v205
	v_fmac_f32_e32 v230, v228, v206
	v_fmac_f32_e32 v231, v228, v207
	v_fmac_f32_e32 v232, v228, v208
	v_fmac_f32_e32 v233, v228, v209
	v_fmac_f32_e32 v230, v229, v210
	v_fmac_f32_e32 v231, v229, v211
	v_fmac_f32_e32 v232, v229, v212
	v_fmac_f32_e32 v233, v229, v213
	global_load_dwordx4 v[214:217], v66, s[16:17] offset:0
	global_load_dwordx4 v[218:221], v66, s[16:17] offset:16
	global_load_dwordx4 v[222:225], v66, s[16:17] offset:32
	global_load_dwordx4 v[226:229], v66, s[16:17] offset:48
	global_load_dwordx4 v[150:153], v65, s[18:19] offset:0
	global_load_dwordx4 v[154:157], v65, s[18:19] offset:1024
	global_load_dwordx4 v[158:161], v65, s[18:19] offset:2048
	global_load_dwordx4 v[162:165], v65, s[18:19] offset:3072
	global_load_dwordx4 v[166:169], v234, s[18:19] offset:0
	global_load_dwordx4 v[170:173], v234, s[18:19] offset:1024
	global_load_dwordx4 v[174:177], v234, s[18:19] offset:2048
	global_load_dwordx4 v[178:181], v234, s[18:19] offset:3072
	global_load_dwordx4 v[182:185], v235, s[18:19] offset:0
	global_load_dwordx4 v[186:189], v235, s[18:19] offset:1024
	global_load_dwordx4 v[190:193], v235, s[18:19] offset:2048
	global_load_dwordx4 v[194:197], v235, s[18:19] offset:3072
	global_load_dwordx4 v[198:201], v236, s[18:19] offset:0
	global_load_dwordx4 v[202:205], v236, s[18:19] offset:1024
	global_load_dwordx4 v[206:209], v236, s[18:19] offset:2048
	global_load_dwordx4 v[210:213], v236, s[18:19] offset:3072
	s_add_u32 s16, s16, 64
	s_addc_u32 s17, s17, 0
	s_add_u32 s18, s18, 0x4000
	s_addc_u32 s19, s19, 0
	s_waitcnt vmcnt(20)
	v_fmac_f32_e32 v230, v134, v70
	v_fmac_f32_e32 v231, v134, v71
	v_fmac_f32_e32 v232, v134, v72
	v_fmac_f32_e32 v233, v134, v73
	v_fmac_f32_e32 v230, v135, v74
	v_fmac_f32_e32 v231, v135, v75
	v_fmac_f32_e32 v232, v135, v76
	v_fmac_f32_e32 v233, v135, v77
	v_fmac_f32_e32 v230, v136, v78
	v_fmac_f32_e32 v231, v136, v79
	v_fmac_f32_e32 v232, v136, v80
	v_fmac_f32_e32 v233, v136, v81
	v_fmac_f32_e32 v230, v137, v82
	v_fmac_f32_e32 v231, v137, v83
	v_fmac_f32_e32 v232, v137, v84
	v_fmac_f32_e32 v233, v137, v85
	v_fmac_f32_e32 v230, v138, v86
	v_fmac_f32_e32 v231, v138, v87
	v_fmac_f32_e32 v232, v138, v88
	v_fmac_f32_e32 v233, v138, v89
	v_fmac_f32_e32 v230, v139, v90
	v_fmac_f32_e32 v231, v139, v91
	v_fmac_f32_e32 v232, v139, v92
	v_fmac_f32_e32 v233, v139, v93
	v_fmac_f32_e32 v230, v140, v94
	v_fmac_f32_e32 v231, v140, v95
	v_fmac_f32_e32 v232, v140, v96
	v_fmac_f32_e32 v233, v140, v97
	v_fmac_f32_e32 v230, v141, v98
	v_fmac_f32_e32 v231, v141, v99
	v_fmac_f32_e32 v232, v141, v100
	v_fmac_f32_e32 v233, v141, v101
	v_fmac_f32_e32 v230, v142, v102
	v_fmac_f32_e32 v231, v142, v103
	v_fmac_f32_e32 v232, v142, v104
	v_fmac_f32_e32 v233, v142, v105
	v_fmac_f32_e32 v230, v143, v106
	v_fmac_f32_e32 v231, v143, v107
	v_fmac_f32_e32 v232, v143, v108
	v_fmac_f32_e32 v233, v143, v109
	v_fmac_f32_e32 v230, v144, v110
	v_fmac_f32_e32 v231, v144, v111
	v_fmac_f32_e32 v232, v144, v112
	v_fmac_f32_e32 v233, v144, v113
	v_fmac_f32_e32 v230, v145, v114
	v_fmac_f32_e32 v231, v145, v115
	v_fmac_f32_e32 v232, v145, v116
	v_fmac_f32_e32 v233, v145, v117
	v_fmac_f32_e32 v230, v146, v118
	v_fmac_f32_e32 v231, v146, v119
	v_fmac_f32_e32 v232, v146, v120
	v_fmac_f32_e32 v233, v146, v121
	v_fmac_f32_e32 v230, v147, v122
	v_fmac_f32_e32 v231, v147, v123
	v_fmac_f32_e32 v232, v147, v124
	v_fmac_f32_e32 v233, v147, v125
	v_fmac_f32_e32 v230, v148, v126
	v_fmac_f32_e32 v231, v148, v127
	v_fmac_f32_e32 v232, v148, v128
	v_fmac_f32_e32 v233, v148, v129
	v_fmac_f32_e32 v230, v149, v130
	v_fmac_f32_e32 v231, v149, v131
	v_fmac_f32_e32 v232, v149, v132
	v_fmac_f32_e32 v233, v149, v133
	global_load_dwordx4 v[134:137], v66, s[16:17] offset:0
	global_load_dwordx4 v[138:141], v66, s[16:17] offset:16
	global_load_dwordx4 v[142:145], v66, s[16:17] offset:32
	global_load_dwordx4 v[146:149], v66, s[16:17] offset:48
	global_load_dwordx4 v[70:73], v65, s[18:19] offset:0
	global_load_dwordx4 v[74:77], v65, s[18:19] offset:1024
	global_load_dwordx4 v[78:81], v65, s[18:19] offset:2048
	global_load_dwordx4 v[82:85], v65, s[18:19] offset:3072
	global_load_dwordx4 v[86:89], v234, s[18:19] offset:0
	global_load_dwordx4 v[90:93], v234, s[18:19] offset:1024
	global_load_dwordx4 v[94:97], v234, s[18:19] offset:2048
	global_load_dwordx4 v[98:101], v234, s[18:19] offset:3072
	global_load_dwordx4 v[102:105], v235, s[18:19] offset:0
	global_load_dwordx4 v[106:109], v235, s[18:19] offset:1024
	global_load_dwordx4 v[110:113], v235, s[18:19] offset:2048
	global_load_dwordx4 v[114:117], v235, s[18:19] offset:3072
	global_load_dwordx4 v[118:121], v236, s[18:19] offset:0
	global_load_dwordx4 v[122:125], v236, s[18:19] offset:1024
	global_load_dwordx4 v[126:129], v236, s[18:19] offset:2048
	global_load_dwordx4 v[130:133], v236, s[18:19] offset:3072
	s_add_u32 s16, s16, 64
	s_addc_u32 s17, s17, 0
	s_add_u32 s18, s18, 0x4000
	s_addc_u32 s19, s19, 0
	s_waitcnt vmcnt(20)
; DI void phase0(const Params& p, unsigned char* lds) {
;     ...
;         const int c = cgp * 64 + (tid & 63), part = tid >> 6;
;         float acc = 0.f;
;         for (int k = part * 512; k < part * 512 + 512; ++k) acc += pos[k] * w1[(size_t)k * 256 + c];
	v_fmac_f32_e32 v230, v214, v150
	v_fmac_f32_e32 v231, v214, v151
	v_fmac_f32_e32 v232, v214, v152
	v_fmac_f32_e32 v233, v214, v153
	v_fmac_f32_e32 v230, v215, v154
	v_fmac_f32_e32 v231, v215, v155
	v_fmac_f32_e32 v232, v215, v156
	v_fmac_f32_e32 v233, v215, v157
	v_fmac_f32_e32 v230, v216, v158
	v_fmac_f32_e32 v231, v216, v159
	v_fmac_f32_e32 v232, v216, v160
	v_fmac_f32_e32 v233, v216, v161
	v_fmac_f32_e32 v230, v217, v162
	v_fmac_f32_e32 v231, v217, v163
	v_fmac_f32_e32 v232, v217, v164
	v_fmac_f32_e32 v233, v217, v165
	v_fmac_f32_e32 v230, v218, v166
	v_fmac_f32_e32 v231, v218, v167
	v_fmac_f32_e32 v232, v218, v168
	v_fmac_f32_e32 v233, v218, v169
	v_fmac_f32_e32 v230, v219, v170
	v_fmac_f32_e32 v231, v219, v171
	v_fmac_f32_e32 v232, v219, v172
	v_fmac_f32_e32 v233, v219, v173
	v_fmac_f32_e32 v230, v220, v174
	v_fmac_f32_e32 v231, v220, v175
	v_fmac_f32_e32 v232, v220, v176
	v_fmac_f32_e32 v233, v220, v177
	v_fmac_f32_e32 v230, v221, v178
	v_fmac_f32_e32 v231, v221, v179
	v_fmac_f32_e32 v232, v221, v180
	v_fmac_f32_e32 v233, v221, v181
	v_fmac_f32_e32 v230, v222, v182
	v_fmac_f32_e32 v231, v222, v183
	v_fmac_f32_e32 v232, v222, v184
	v_fmac_f32_e32 v233, v222, v185
	v_fmac_f32_e32 v230, v223, v186
	v_fmac_f32_e32 v231, v223, v187
	v_fmac_f32_e32 v232, v223, v188
	v_fmac_f32_e32 v233, v223, v189
	v_fmac_f32_e32 v230, v224, v190
	v_fmac_f32_e32 v231, v224, v191
	v_fmac_f32_e32 v232, v224, v192
	v_fmac_f32_e32 v233, v224, v193
	v_fmac_f32_e32 v230, v225, v194
	v_fmac_f32_e32 v231, v225, v195
	v_fmac_f32_e32 v232, v225, v196
	v_fmac_f32_e32 v233, v225, v197
	v_fmac_f32_e32 v230, v226, v198
	v_fmac_f32_e32 v231, v226, v199
	v_fmac_f32_e32 v232, v226, v200
	v_fmac_f32_e32 v233, v226, v201
	v_fmac_f32_e32 v230, v227, v202
	v_fmac_f32_e32 v231, v227, v203
	v_fmac_f32_e32 v232, v227, v204
	v_fmac_f32_e32 v233, v227, v205
	v_fmac_f32_e32 v230, v228, v206
	v_fmac_f32_e32 v231, v228, v207
	v_fmac_f32_e32 v232, v228, v208
	v_fmac_f32_e32 v233, v228, v209
	v_fmac_f32_e32 v230, v229, v210
	v_fmac_f32_e32 v231, v229, v211
	v_fmac_f32_e32 v232, v229, v212
	v_fmac_f32_e32 v233, v229, v213
	global_load_dwordx4 v[214:217], v66, s[16:17] offset:0
	global_load_dwordx4 v[218:221], v66, s[16:17] offset:16
	global_load_dwordx4 v[222:225], v66, s[16:17] offset:32
	global_load_dwordx4 v[226:229], v66, s[16:17] offset:48
	global_load_dwordx4 v[150:153], v65, s[18:19] offset:0
	global_load_dwordx4 v[154:157], v65, s[18:19] offset:1024
	global_load_dwordx4 v[158:161], v65, s[18:19] offset:2048
	global_load_dwordx4 v[162:165], v65, s[18:19] offset:3072
	global_load_dwordx4 v[166:169], v234, s[18:19] offset:0
	global_load_dwordx4 v[170:173], v234, s[18:19] offset:1024
	global_load_dwordx4 v[174:177], v234, s[18:19] offset:2048
	global_load_dwordx4 v[178:181], v234, s[18:19] offset:3072
	global_load_dwordx4 v[182:185], v235, s[18:19] offset:0
	global_load_dwordx4 v[186:189], v235, s[18:19] offset:1024
	global_load_dwordx4 v[190:193], v235, s[18:19] offset:2048
	global_load_dwordx4 v[194:197], v235, s[18:19] offset:3072
	global_load_dwordx4 v[198:201], v236, s[18:19] offset:0
	global_load_dwordx4 v[202:205], v236, s[18:19] offset:1024
	global_load_dwordx4 v[206:209], v236, s[18:19] offset:2048
	global_load_dwordx4 v[210:213], v236, s[18:19] offset:3072
	s_add_u32 s16, s16, 64
	s_addc_u32 s17, s17, 0
	s_add_u32 s18, s18, 0x4000
	s_addc_u32 s19, s19, 0
	s_waitcnt vmcnt(20)
; DI void phase0(const Params& p, unsigned char* lds) {
;     ...
;         for (int k = part * 512; k < part * 512 + 512; ++k) acc += pos[k] * w1[(size_t)k * 256 + c];
;         __syncthreads();
;         tl[part * 64 + (tid & 63)] = acc;
;         __syncthreads();
	v_fmac_f32_e32 v230, v134, v70
	v_fmac_f32_e32 v231, v134, v71
	v_fmac_f32_e32 v232, v134, v72
	v_fmac_f32_e32 v233, v134, v73
	v_fmac_f32_e32 v230, v135, v74
	v_fmac_f32_e32 v231, v135, v75
	v_fmac_f32_e32 v232, v135, v76
	v_fmac_f32_e32 v233, v135, v77
	v_fmac_f32_e32 v230, v136, v78
	v_fmac_f32_e32 v231, v136, v79
	v_fmac_f32_e32 v232, v136, v80
	v_fmac_f32_e32 v233, v136, v81
	v_fmac_f32_e32 v230, v137, v82
	v_fmac_f32_e32 v231, v137, v83
	v_fmac_f32_e32 v232, v137, v84
	v_fmac_f32_e32 v233, v137, v85
	v_fmac_f32_e32 v230, v138, v86
	v_fmac_f32_e32 v231, v138, v87
	v_fmac_f32_e32 v232, v138, v88
	v_fmac_f32_e32 v233, v138, v89
	v_fmac_f32_e32 v230, v139, v90
	v_fmac_f32_e32 v231, v139, v91
	v_fmac_f32_e32 v232, v139, v92
	v_fmac_f32_e32 v233, v139, v93
	v_fmac_f32_e32 v230, v140, v94
	v_fmac_f32_e32 v231, v140, v95
	v_fmac_f32_e32 v232, v140, v96
	v_fmac_f32_e32 v233, v140, v97
	v_fmac_f32_e32 v230, v141, v98
	v_fmac_f32_e32 v231, v141, v99
	v_fmac_f32_e32 v232, v141, v100
	v_fmac_f32_e32 v233, v141, v101
	v_fmac_f32_e32 v230, v142, v102
	v_fmac_f32_e32 v231, v142, v103
	v_fmac_f32_e32 v232, v142, v104
	v_fmac_f32_e32 v233, v142, v105
	v_fmac_f32_e32 v230, v143, v106
	v_fmac_f32_e32 v231, v143, v107
	v_fmac_f32_e32 v232, v143, v108
	v_fmac_f32_e32 v233, v143, v109
	v_fmac_f32_e32 v230, v144, v110
	v_fmac_f32_e32 v231, v144, v111
	v_fmac_f32_e32 v232, v144, v112
	v_fmac_f32_e32 v233, v144, v113
	v_fmac_f32_e32 v230, v145, v114
	v_fmac_f32_e32 v231, v145, v115
	v_fmac_f32_e32 v232, v145, v116
	v_fmac_f32_e32 v233, v145, v117
	v_fmac_f32_e32 v230, v146, v118
	v_fmac_f32_e32 v231, v146, v119
	v_fmac_f32_e32 v232, v146, v120
	v_fmac_f32_e32 v233, v146, v121
	v_fmac_f32_e32 v230, v147, v122
	v_fmac_f32_e32 v231, v147, v123
	v_fmac_f32_e32 v232, v147, v124
	v_fmac_f32_e32 v233, v147, v125
	v_fmac_f32_e32 v230, v148, v126
	v_fmac_f32_e32 v231, v148, v127
	v_fmac_f32_e32 v232, v148, v128
	v_fmac_f32_e32 v233, v148, v129
	v_fmac_f32_e32 v230, v149, v130
	v_fmac_f32_e32 v231, v149, v131
	v_fmac_f32_e32 v232, v149, v132
	v_fmac_f32_e32 v233, v149, v133
	s_waitcnt vmcnt(0)
	v_fmac_f32_e32 v230, v214, v150
	v_fmac_f32_e32 v231, v214, v151
	v_fmac_f32_e32 v232, v214, v152
	v_fmac_f32_e32 v233, v214, v153
	v_fmac_f32_e32 v230, v215, v154
	v_fmac_f32_e32 v231, v215, v155
	v_fmac_f32_e32 v232, v215, v156
	v_fmac_f32_e32 v233, v215, v157
	v_fmac_f32_e32 v230, v216, v158
	v_fmac_f32_e32 v231, v216, v159
	v_fmac_f32_e32 v232, v216, v160
	v_fmac_f32_e32 v233, v216, v161
	v_fmac_f32_e32 v230, v217, v162
	v_fmac_f32_e32 v231, v217, v163
	v_fmac_f32_e32 v232, v217, v164
	v_fmac_f32_e32 v233, v217, v165
	v_fmac_f32_e32 v230, v218, v166
	v_fmac_f32_e32 v231, v218, v167
	v_fmac_f32_e32 v232, v218, v168
	v_fmac_f32_e32 v233, v218, v169
	v_fmac_f32_e32 v230, v219, v170
	v_fmac_f32_e32 v231, v219, v171
	v_fmac_f32_e32 v232, v219, v172
	v_fmac_f32_e32 v233, v219, v173
	v_fmac_f32_e32 v230, v220, v174
	v_fmac_f32_e32 v231, v220, v175
	v_fmac_f32_e32 v232, v220, v176
	v_fmac_f32_e32 v233, v220, v177
	v_fmac_f32_e32 v230, v221, v178
	v_fmac_f32_e32 v231, v221, v179
	v_fmac_f32_e32 v232, v221, v180
	v_fmac_f32_e32 v233, v221, v181
	v_fmac_f32_e32 v230, v222, v182
	v_fmac_f32_e32 v231, v222, v183
	v_fmac_f32_e32 v232, v222, v184
	v_fmac_f32_e32 v233, v222, v185
	v_fmac_f32_e32 v230, v223, v186
	v_fmac_f32_e32 v231, v223, v187
	v_fmac_f32_e32 v232, v223, v188
	v_fmac_f32_e32 v233, v223, v189
	v_fmac_f32_e32 v230, v224, v190
	v_fmac_f32_e32 v231, v224, v191
	v_fmac_f32_e32 v232, v224, v192
	v_fmac_f32_e32 v233, v224, v193
	v_fmac_f32_e32 v230, v225, v194
	v_fmac_f32_e32 v231, v225, v195
	v_fmac_f32_e32 v232, v225, v196
	v_fmac_f32_e32 v233, v225, v197
	v_fmac_f32_e32 v230, v226, v198
	v_fmac_f32_e32 v231, v226, v199
	v_fmac_f32_e32 v232, v226, v200
	v_fmac_f32_e32 v233, v226, v201
	v_fmac_f32_e32 v230, v227, v202
	v_fmac_f32_e32 v231, v227, v203
	v_fmac_f32_e32 v232, v227, v204
	v_fmac_f32_e32 v233, v227, v205
	v_fmac_f32_e32 v230, v228, v206
	v_fmac_f32_e32 v231, v228, v207
	v_fmac_f32_e32 v232, v228, v208
	v_fmac_f32_e32 v233, v228, v209
	v_fmac_f32_e32 v230, v229, v210
	v_fmac_f32_e32 v231, v229, v211
	v_fmac_f32_e32 v232, v229, v212
	v_fmac_f32_e32 v233, v229, v213
	s_lshl_b32 s22, s5, 10
	v_lshl_add_u32 v67, v63, 8, s22
	v_lshl_add_u32 v67, v62, 4, v67
	v_add_u32_e32 v67, v32, v67
	s_barrier
	ds_write_b128 v67, v[230:233]
	s_waitcnt lgkmcnt(0)
	s_barrier
	s_and_saveexec_b64 s[10:11], s[0:1]
	s_cbranch_execz .Lb1_done
	v_lshl_add_u32 v68, v28, 2, v32

; DI void phase0(const Params& p, unsigned char* lds) {
;     ...
;         __syncthreads();
;         if (tid < 64) ((float*)(ws + OFF_B1))[kv * 256 + c] = (tl[tid] + tl[64 + tid]) + (tl[128 + tid] + tl[192 + tid]);
	ds_read_b32 v70, v68 offset:0
	ds_read_b32 v71, v68 offset:256
	ds_read_b32 v72, v68 offset:512
	ds_read_b32 v73, v68 offset:768
	ds_read_b32 v74, v68 offset:1024
	ds_read_b32 v75, v68 offset:1280
	ds_read_b32 v76, v68 offset:1536
	ds_read_b32 v77, v68 offset:1792
	ds_read_b32 v78, v68 offset:2048
	ds_read_b32 v79, v68 offset:2304
	ds_read_b32 v80, v68 offset:2560
	ds_read_b32 v81, v68 offset:2816
	ds_read_b32 v82, v68 offset:3072
	ds_read_b32 v83, v68 offset:3328
	ds_read_b32 v84, v68 offset:3584
	ds_read_b32 v85, v68 offset:3840
	s_waitcnt lgkmcnt(0)
	v_add_f32_e32 v70, v70, v78
	v_add_f32_e32 v71, v71, v79
	v_add_f32_e32 v72, v72, v80
	v_add_f32_e32 v73, v73, v81
	v_add_f32_e32 v74, v74, v82
	v_add_f32_e32 v75, v75, v83
	v_add_f32_e32 v76, v76, v84
	v_add_f32_e32 v77, v77, v85
	v_add_f32_e32 v70, v70, v74
	v_add_f32_e32 v71, v71, v75
	v_add_f32_e32 v72, v72, v76
	v_add_f32_e32 v73, v73, v77
	v_add_f32_e32 v70, v70, v72
	v_add_f32_e32 v71, v71, v73
	v_add_f32_e32 v70, v70, v71
	s_lshl_b32 s23, s4, 8
	v_lshl_add_u32 v69, v28, 2, s23
	s_add_u32 s24, s88, 0x1aa5000
	s_addc_u32 s25, s89, 0
	global_store_dword v69, v70, s[24:25]
.Lb1_done:
	s_or_b64 exec, exec, s[10:11]
	s_barrier


; DI void phase0(const Params& p, unsigned char* lds) {
;     ...
;     {
;         const float* x = p.in[0]; const float* g = p.in[1];
;         bf16_t* H = (bf16_t*)(ws + OFF_H);
;         for (int row = VBLK * 4 + w; row < T; row += G * 4) {
;             const float* xr = x + (size_t)row * 1024;
;             f32x4 v[4]; float ss = 0.f;
.LBB0_126:
	s_or_b64 exec, exec, s[2:3]
	v_lshrrev_b32_e32 v3, 6, v1
	v_and_b32_e32 v3, 12, v3
	v_readlane_b32 s0, v238, 0
	v_lshrrev_b32_e32 v2, 6, v28
	s_nop 0
	v_lshl_add_u32 v3, s0, 3, v3
	v_or_b32_e32 v2, v3, v2
	s_mov_b32 s0, 0x8000
	v_cmp_gt_i32_e32 vcc, s0, v2
	s_and_saveexec_b64 s[0:1], vcc
	s_cbranch_execz .LBB0_129
	v_mbcnt_lo_u32_b32 v3, -1, 0
	v_mbcnt_hi_u32_b32 v3, -1, v3
	v_and_b32_e32 v5, 64, v3
	v_xor_b32_e32 v4, 32, v3
	v_add_u32_e32 v5, 64, v5
	v_cmp_lt_i32_e32 vcc, v4, v5
	v_readlane_b32 s8, v238, 15
	v_readlane_b32 s2, v238, 10
	v_cndmask_b32_e32 v4, v3, v4, vcc
	v_lshlrev_b32_e32 v10, 2, v4
	v_xor_b32_e32 v4, 16, v3
	v_cmp_lt_i32_e32 vcc, v4, v5
	v_readlane_b32 s9, v238, 16
	v_readlane_b32 s3, v238, 11
	v_cndmask_b32_e32 v4, v3, v4, vcc
	v_lshlrev_b32_e32 v11, 2, v4
	v_xor_b32_e32 v4, 8, v3
	v_cmp_lt_i32_e32 vcc, v4, v5
	s_lshl_b32 s2, s2, 3
	v_readlane_b32 s10, v238, 17
	v_cndmask_b32_e32 v4, v3, v4, vcc
	v_lshlrev_b32_e32 v12, 2, v4
	v_xor_b32_e32 v4, 4, v3
	v_cmp_lt_i32_e32 vcc, v4, v5
	v_readlane_b32 s11, v238, 18
	s_mov_b64 s[4:5], 0x1ba5800
	v_cndmask_b32_e32 v4, v3, v4, vcc
	v_lshlrev_b32_e32 v14, 2, v4
	v_xor_b32_e32 v4, 2, v3
	v_cmp_lt_i32_e32 vcc, v4, v5
	s_ashr_i32 s3, s2, 31
	s_mov_b64 s[6:7], 0xc00
	v_cndmask_b32_e32 v4, v3, v4, vcc
	v_lshlrev_b32_e32 v15, 2, v4
	v_xor_b32_e32 v4, 1, v3
	v_cmp_lt_i32_e32 vcc, v4, v5
	v_mov_b32_e32 v5, 0
	v_readlane_b32 s12, v238, 19
	v_cndmask_b32_e32 v3, v3, v4, vcc
	v_lshlrev_b32_e32 v16, 2, v3
	v_ashrrev_i32_e32 v3, 31, v2
	v_lshlrev_b32_e32 v4, 4, v13
	v_lshlrev_b64 v[6:7], 11, v[2:3]
	v_and_b32_e32 v13, 63, v1
	v_lshlrev_b64 v[8:9], 12, v[2:3]
	v_lshl_or_b32 v6, v13, 3, v6
	v_lshl_or_b32 v8, v13, 4, v8
	v_lshl_add_u64 v[6:7], s[88:89], 0, v[6:7]
	v_lshl_add_u64 v[8:9], s[8:9], 0, v[8:9]
	v_lshl_add_u64 v[4:5], s[10:11], 0, v[4:5]
	v_lshl_add_u64 v[6:7], v[6:7], 0, s[4:5]
	s_lshl_b64 s[4:5], s[2:3], 11
	v_lshl_add_u64 v[8:9], v[8:9], 0, s[6:7]
	s_lshl_b64 s[6:7], s[2:3], 12
	s_mov_b64 s[8:9], 0
	v_mov_b32_e32 v3, 0x358637bd
	s_mov_b32 s3, 0x800000
	s_movk_i32 s10, 0x7fff
	v_readlane_b32 s13, v238, 20
	v_readlane_b32 s14, v238, 21
	v_readlane_b32 s15, v238, 22
	v_readlane_b32 s16, v238, 23
	v_readlane_b32 s17, v238, 24
	v_readlane_b32 s18, v238, 25
	v_readlane_b32 s19, v238, 26
	v_readlane_b32 s20, v238, 27
	v_readlane_b32 s21, v238, 28
	v_readlane_b32 s22, v238, 29
	v_readlane_b32 s23, v238, 30
	v_readfirstlane_b32 s24, v2
	s_nop 3
	s_cmp_lt_u32 s24, 32
	s_cbranch_scc1 .LBB0_129
	global_load_dwordx4 v[200:203], v[4:5], off
	global_load_dwordx4 v[204:207], v[4:5], off offset:1024
	global_load_dwordx4 v[208:211], v[4:5], off offset:2048
	global_load_dwordx4 v[212:215], v[4:5], off offset:3072
	s_mov_b32 s25, s24
	s_cmpk_ge_u32 s24, 0x220
	s_cbranch_scc1 .Lrn_first
	s_sub_u32 s26, s24, 32
	s_and_b32 s27, s26, 31
	s_lshr_b32 s26, s26, 5
	s_lshl_b32 s26, s26, 11
	s_add_u32 s25, s27, s26
.Lrn_first:

; DI void phase0(const Params& p, unsigned char* lds) {
;     ...
;         for (int row = VBLK * 4 + w; row < T; row += G * 4) {
;             const float* xr = x + (size_t)row * 1024;
;             f32x4 v[4]; float ss = 0.f;
; #pragma unroll
;             for (int i = 0; i < 4; ++i) { v[i] = *(const f32x4*)(xr + i * 256 + lane * 4); ss += v[i][0] * v[i][0] + v[i][1] * v[i][1] + v[i][2] * v[i][2] + v[i][3] * v[i][3]; }
	s_sub_i32 s28, s25, s24
	s_mul_hi_i32 s29, s28, 0x1000
	s_mul_i32 s28, s28, 0x1000
	v_lshl_add_u64 v[56:57], v[8:9], 0, s[28:29]
	global_load_dwordx4 v[216:219], v[56:57], off offset:-3072
	global_load_dwordx4 v[220:223], v[56:57], off offset:-2048
	global_load_dwordx4 v[224:227], v[56:57], off offset:-1024
	global_load_dwordx4 v[228:231], v[56:57], off

; DI void phase0(const Params& p, unsigned char* lds) {
;     ...
;         for (int row = VBLK * 4 + w; row < T; row += G * 4) {
	s_waitcnt vmcnt(0)
.Lrn_loop:

; DI void phase0(const Params& p, unsigned char* lds) {
;     ...
;         for (int row = VBLK * 4 + w; row < T; row += G * 4) {
;             const float* xr = x + (size_t)row * 1024;
;             f32x4 v[4]; float ss = 0.f;
; #pragma unroll
;             for (int i = 0; i < 4; ++i) { v[i] = *(const f32x4*)(xr + i * 256 + lane * 4); ss += v[i][0] * v[i][0] + v[i][1] * v[i][1] + v[i][2] * v[i][2] + v[i][3] * v[i][3]; }
	v_mov_b32_e32 v18, v216
	v_mov_b32_e32 v19, v217
	v_mov_b32_e32 v20, v218
	v_mov_b32_e32 v21, v219
	v_mov_b32_e32 v22, v220
	v_mov_b32_e32 v23, v221
	v_mov_b32_e32 v24, v222
	v_mov_b32_e32 v25, v223
	v_mov_b32_e32 v26, v224
	v_mov_b32_e32 v27, v225
	v_mov_b32_e32 v28, v226
	v_mov_b32_e32 v29, v227
	v_mov_b32_e32 v30, v228
	v_mov_b32_e32 v31, v229
	v_mov_b32_e32 v32, v230
	v_mov_b32_e32 v33, v231
	s_sub_i32 s28, s25, s24
	s_mul_hi_i32 s29, s28, 0x800
	s_mul_i32 s28, s28, 0x800
	v_lshl_add_u64 v[58:59], v[6:7], 0, s[28:29]
	s_add_u32 s26, s25, 0x800
	s_and_b32 s27, s25, 0x7ff
	s_cmp_lt_u32 s27, 32
	s_cselect_b32 s26, s24, s26
	s_cmp_lt_u32 s26, 0x8000
	s_cselect_b32 s30, 1, 0
	s_cbranch_scc0 .Lrn_nopf

; DI void phase0(const Params& p, unsigned char* lds) {
;     ...
;             for (int i = 0; i < 4; ++i) { v[i] = *(const f32x4*)(xr + i * 256 + lane * 4); ss += v[i][0] * v[i][0] + v[i][1] * v[i][1] + v[i][2] * v[i][2] + v[i][3] * v[i][3]; }
	s_sub_i32 s28, s26, s24
	s_mul_hi_i32 s29, s28, 0x1000
	s_mul_i32 s28, s28, 0x1000
	v_lshl_add_u64 v[56:57], v[8:9], 0, s[28:29]
	global_load_dwordx4 v[216:219], v[56:57], off offset:-3072
	global_load_dwordx4 v[220:223], v[56:57], off offset:-2048
	global_load_dwordx4 v[224:227], v[56:57], off offset:-1024
	global_load_dwordx4 v[228:231], v[56:57], off

; DI unsigned pk_bf16(float a, float b) { f32x2 v = {a, b}; return __builtin_bit_cast(unsigned, __builtin_convertvector(v, bf16v2)); }
; DI void phase0(const Params& p, unsigned char* lds) {
;     ...
;             for (int i = 0; i < 4; ++i) { v[i] = *(const f32x4*)(xr + i * 256 + lane * 4); ss += v[i][0] * v[i][0] + v[i][1] * v[i][1] + v[i][2] * v[i][2] + v[i][3] * v[i][3]; }
;             ss = wave_sum(ss);
;             const float rstd = rsqrtf(ss * (1.f / 1024.f) + NORM_EPS);
; #pragma unroll
;             for (int i = 0; i < 4; ++i) {
;                 const f32x4 gg = *(const f32x4*)(g + i * 256 + lane * 4);
;                 u32x2 o; o.x = pk_bf16(v[i][0] * rstd * gg[0], v[i][1] * rstd * gg[1]); o.y = pk_bf16(v[i][2] * rstd * gg[2], v[i][3] * rstd * gg[3]);
;                 *(u32x2*)(H + (size_t)row * 1024 + i * 256 + lane * 4) = o;
;             }
.Lrn_nopf:
	v_mul_f32_e32 v40, v18, v18
	v_fmac_f32_e32 v40, v19, v19
	v_fmac_f32_e32 v40, v20, v20
	v_fmac_f32_e32 v40, v21, v21
	v_mul_f32_e32 v41, v22, v22
	v_fmac_f32_e32 v41, v23, v23
	v_fmac_f32_e32 v41, v24, v24
	v_fmac_f32_e32 v41, v25, v25
	v_mul_f32_e32 v42, v26, v26
	v_fmac_f32_e32 v42, v27, v27
	v_fmac_f32_e32 v42, v28, v28
	v_fmac_f32_e32 v42, v29, v29
	v_mul_f32_e32 v43, v30, v30
	v_fmac_f32_e32 v43, v31, v31
	v_fmac_f32_e32 v43, v32, v32
	v_fmac_f32_e32 v43, v33, v33
	v_add_f32_e32 v40, v40, v41
	v_add_f32_e32 v42, v42, v43
	v_add_f32_e32 v13, v40, v42
	ds_bpermute_b32 v17, v10, v13
	s_waitcnt lgkmcnt(0)
	v_add_f32_e32 v13, v13, v17
	ds_bpermute_b32 v17, v11, v13
	s_waitcnt lgkmcnt(0)
	v_add_f32_e32 v13, v13, v17
	ds_bpermute_b32 v17, v12, v13
	s_waitcnt lgkmcnt(0)
	v_add_f32_e32 v13, v13, v17
	ds_bpermute_b32 v17, v14, v13
	s_waitcnt lgkmcnt(0)
	v_add_f32_e32 v13, v13, v17
	ds_bpermute_b32 v17, v15, v13
	s_waitcnt lgkmcnt(0)
	v_add_f32_e32 v13, v13, v17
	ds_bpermute_b32 v17, v16, v13
	s_waitcnt lgkmcnt(0)
	v_add_f32_e32 v13, v13, v17
	v_fmamk_f32 v13, v13, 0x3a800000, v3
	v_mul_f32_e32 v17, 0x4b800000, v13
	v_cmp_gt_f32_e32 vcc, s3, v13
	s_nop 1
	v_cndmask_b32_e32 v13, v13, v17, vcc
	v_rsq_f32_e32 v13, v13
	s_nop 0
	v_mul_f32_e32 v17, 0x45800000, v13
	v_cndmask_b32_e32 v38, v13, v17, vcc
	v_mul_f32_e32 v18, v18, v38
	v_mul_f32_e32 v19, v19, v38
	v_mul_f32_e32 v20, v20, v38
	v_mul_f32_e32 v21, v21, v38
	v_mul_f32_e32 v18, v200, v18
	v_mul_f32_e32 v19, v201, v19
	v_mul_f32_e32 v20, v202, v20
	v_mul_f32_e32 v21, v203, v21
	v_cvt_pk_bf16_f32 v44, v18, v19
	v_cvt_pk_bf16_f32 v45, v20, v21
	global_store_dwordx2 v[58:59], v[44:45], off
	v_mul_f32_e32 v22, v22, v38
	v_mul_f32_e32 v23, v23, v38
	v_mul_f32_e32 v24, v24, v38
	v_mul_f32_e32 v25, v25, v38
	v_mul_f32_e32 v22, v204, v22
	v_mul_f32_e32 v23, v205, v23
	v_mul_f32_e32 v24, v206, v24
	v_mul_f32_e32 v25, v207, v25
	v_cvt_pk_bf16_f32 v46, v22, v23
	v_cvt_pk_bf16_f32 v47, v24, v25
	global_store_dwordx2 v[58:59], v[46:47], off offset:512
	v_mul_f32_e32 v26, v26, v38
	v_mul_f32_e32 v27, v27, v38
	v_mul_f32_e32 v28, v28, v38
	v_mul_f32_e32 v29, v29, v38
	v_mul_f32_e32 v26, v208, v26
	v_mul_f32_e32 v27, v209, v27
	v_mul_f32_e32 v28, v210, v28
	v_mul_f32_e32 v29, v211, v29
	v_cvt_pk_bf16_f32 v48, v26, v27
	v_cvt_pk_bf16_f32 v49, v28, v29
	global_store_dwordx2 v[58:59], v[48:49], off offset:1024
	v_mul_f32_e32 v30, v30, v38
	v_mul_f32_e32 v31, v31, v38
	v_mul_f32_e32 v32, v32, v38
	v_mul_f32_e32 v33, v33, v38
	v_mul_f32_e32 v30, v212, v30
	v_mul_f32_e32 v31, v213, v31
	v_mul_f32_e32 v32, v214, v32
	v_mul_f32_e32 v33, v215, v33
	v_cvt_pk_bf16_f32 v50, v30, v31
	v_cvt_pk_bf16_f32 v51, v32, v33
	global_store_dwordx2 v[58:59], v[50:51], off offset:1536
	s_mov_b32 s25, s26
	s_waitcnt vmcnt(4)
	s_cmp_lg_u32 s30, 0
	s_cbranch_scc1 .Lrn_loop

